# conv task prologue halo loads issued together; attention combine loads issued together
# baseline (speedup 1.0000x reference)
; __device__ __forceinline__ void phase_conv(const Params& p, int layer) {
;     ...
;         const int cv = task % NCV, ch = task / NCV, c = cv * 8, r0 = ch * RCH;
;         float wg[3][8], wu[3][8], bg[8], bu[8];
; #pragma unroll
;         for (int j = 0; j < 3; ++j)
; #pragma unroll
;             for (int e = 0; e < 8; e += 4) { *(f32x4*)&wg[j][e] = *(const f32x4*)(wc + j * DFF2 + c + e); *(f32x4*)&wu[j][e] = *(const f32x4*)(wc + j * DFF2 + DFF + c + e); }
; #pragma unroll
;         for (int e = 0; e < 8; e += 4) { *(f32x4*)&bg[e] = *(const f32x4*)(bc + c + e); *(f32x4*)&bu[e] = *(const f32x4*)(bc + DFF + c + e); }
;         float g2[8], g1[8], u2[8], u1[8];
;         if (r0 >= 2) {
;             unpack8(__builtin_nontemporal_load((const u32x4*)(U + (size_t)(r0 - 2) * DFF2 + c)), g2); unpack8(__builtin_nontemporal_load((const u32x4*)(U + (size_t)(r0 - 2) * DFF2 + DFF + c)), u2);
;             unpack8(__builtin_nontemporal_load((const u32x4*)(U + (size_t)(r0 - 1) * DFF2 + c)), g1); unpack8(__builtin_nontemporal_load((const u32x4*)(U + (size_t)(r0 - 1) * DFF2 + DFF + c)), u1);
;         } else {
; #pragma unroll
;             for (int e = 0; e < 8; ++e) { g2[e] = 0.f; g1[e] = 0.f; u2[e] = 0.f; u1[e] = 0.f; }
;         }
.LBB0_387:
	s_mov_b32 s2, 0x2e8ba2e9
	v_mul_hi_i32 v2, v0, s2
	v_lshrrev_b32_e32 v3, 31, v2
	v_ashrrev_i32_e32 v2, 7, v2
	v_add_u32_e32 v38, v2, v3
	v_mul_i32_i24_e32 v2, 0x2c0, v38
	v_lshlrev_b32_e32 v2, 3, v2
	v_sub_u32_e32 v34, v178, v2
	v_ashrrev_i32_e32 v35, 31, v34
	v_lshlrev_b64 v[14:15], 2, v[34:35]
	v_lshl_add_u64 v[6:7], s[10:11], 0, v[14:15]
	v_lshl_add_u64 v[8:9], s[42:43], 0, v[14:15]
	v_lshl_add_u64 v[10:11], s[44:45], 0, v[14:15]
	v_lshl_add_u64 v[12:13], s[48:49], 0, v[14:15]
	v_lshl_add_u64 v[16:17], s[50:51], 0, v[14:15]
	v_lshl_add_u64 v[30:31], s[52:53], 0, v[14:15]
	global_load_dwordx4 v[2:5], v[6:7], off offset:16
	global_load_dwordx4 v[18:21], v[6:7], off
	global_load_dwordx4 v[90:93], v[8:9], off offset:16
	global_load_dwordx4 v[114:117], v[8:9], off
	s_nop 0
	global_load_dwordx4 v[6:9], v[10:11], off offset:16
	global_load_dwordx4 v[22:25], v[10:11], off
	global_load_dwordx4 v[82:85], v[12:13], off offset:16
	global_load_dwordx4 v[106:109], v[12:13], off
	s_nop 0
	global_load_dwordx4 v[10:13], v[16:17], off offset:16
	global_load_dwordx4 v[26:29], v[16:17], off
	global_load_dwordx4 v[86:89], v[30:31], off offset:16
	global_load_dwordx4 v[110:113], v[30:31], off
	v_lshl_add_u64 v[30:31], s[16:17], 0, v[14:15]
	v_lshl_add_u64 v[36:37], s[36:37], 0, v[14:15]
	global_load_dwordx4 v[14:17], v[30:31], off offset:16
	s_nop 0
	global_load_dwordx4 v[30:33], v[30:31], off
	s_nop 0
	global_load_dwordx4 v[94:97], v[36:37], off offset:16
	s_waitcnt lgkmcnt(0)
	global_load_dwordx4 v[118:121], v[36:37], off
	s_movk_i32 s2, 0x2bf
	v_lshlrev_b32_e32 v179, 4, v38
	v_cmp_lt_i32_e32 vcc, s2, v0
	v_mov_b32_e32 v148, 0
	v_lshlrev_b64 v[144:145], 1, v[34:35]
	v_mov_b32_e32 v150, 0
	v_mov_b32_e32 v152, 0
	v_mov_b32_e32 v154, 0
	v_mov_b32_e32 v156, 0
	v_mov_b32_e32 v158, 0
	v_mov_b32_e32 v160, 0
	v_mov_b32_e32 v164, 0
	v_mov_b32_e32 v165, 0
	v_mov_b32_e32 v161, 0
	v_mov_b32_e32 v159, 0
	v_mov_b32_e32 v157, 0
	v_mov_b32_e32 v155, 0
	v_mov_b32_e32 v153, 0
	v_mov_b32_e32 v151, 0
	v_mov_b32_e32 v149, 0
	v_mov_b32_e32 v140, 0
	v_mov_b32_e32 v141, 0
	v_mov_b32_e32 v162, 0
	v_mov_b32_e32 v163, 0
	v_mov_b32_e32 v166, 0
	v_mov_b32_e32 v167, 0
	v_mov_b32_e32 v142, 0
	v_mov_b32_e32 v143, 0
	v_mov_b32_e32 v172, 0
	v_mov_b32_e32 v173, 0
	v_mov_b32_e32 v168, 0
	v_mov_b32_e32 v169, 0
	v_mov_b32_e32 v136, 0
	v_mov_b32_e32 v137, 0
	v_mov_b32_e32 v174, 0
	v_mov_b32_e32 v175, 0
	s_and_saveexec_b64 s[18:19], vcc
	s_cbranch_execz .LBB0_386
	v_add_u32_e32 v34, -2, v179
	v_mov_b64_e32 v[42:43], s[4:5]
	s_movk_i32 s6, 0x5800
	v_mad_u64_u32 v[34:35], s[2:3], v34, s6, v[42:43]
	v_lshl_add_u64 v[38:39], v[34:35], 0, v[144:145]
	global_load_dwordx4 v[224:227], v[38:39], off nt
	v_add_co_u32_e32 v38, vcc, 0x2000, v38
	s_nop 1
	v_addc_co_u32_e32 v39, vcc, 0, v39, vcc
	global_load_dwordx4 v[228:231], v[38:39], off offset:3072 nt
	v_add_u32_e32 v34, -1, v179
	s_nop 0
	v_mad_u64_u32 v[34:35], s[2:3], v34, s6, v[42:43]
	v_lshl_add_u64 v[38:39], v[34:35], 0, v[144:145]
	global_load_dwordx4 v[232:235], v[38:39], off nt
	s_movk_i32 s2, 0x2000
	v_add_co_u32_e32 v34, vcc, s2, v38
	s_nop 1
	v_addc_co_u32_e32 v35, vcc, 0, v39, vcc
	global_load_dwordx4 v[236:239], v[34:35], off offset:3072 nt
	s_waitcnt vmcnt(0)
	v_lshlrev_b32_e32 v137, 16, v224
	v_and_b32_e32 v175, 0xffff0000, v224
	v_lshlrev_b32_e32 v173, 16, v225
	v_and_b32_e32 v169, 0xffff0000, v225
	v_lshlrev_b32_e32 v167, 16, v226
	v_and_b32_e32 v143, 0xffff0000, v226
	v_lshlrev_b32_e32 v141, 16, v227
	v_and_b32_e32 v163, 0xffff0000, v227
	v_lshlrev_b32_e32 v136, 16, v228
	v_and_b32_e32 v174, 0xffff0000, v228
	v_lshlrev_b32_e32 v172, 16, v229
	v_and_b32_e32 v168, 0xffff0000, v229
	v_lshlrev_b32_e32 v166, 16, v230
	v_and_b32_e32 v142, 0xffff0000, v230
	v_lshlrev_b32_e32 v140, 16, v231
	v_and_b32_e32 v162, 0xffff0000, v231
	v_lshlrev_b32_e32 v165, 16, v232
	v_and_b32_e32 v161, 0xffff0000, v232
	v_lshlrev_b32_e32 v159, 16, v233
	v_and_b32_e32 v157, 0xffff0000, v233
	v_lshlrev_b32_e32 v155, 16, v234
	v_and_b32_e32 v153, 0xffff0000, v234
	v_lshlrev_b32_e32 v151, 16, v235
	v_and_b32_e32 v149, 0xffff0000, v235
	v_lshlrev_b32_e32 v164, 16, v236
	v_and_b32_e32 v160, 0xffff0000, v236
	v_lshlrev_b32_e32 v158, 16, v237
	v_and_b32_e32 v156, 0xffff0000, v237
	v_lshlrev_b32_e32 v154, 16, v238
	v_and_b32_e32 v152, 0xffff0000, v238
	v_lshlrev_b32_e32 v150, 16, v239
	v_and_b32_e32 v148, 0xffff0000, v239
	s_branch .LBB0_386

; __device__ __forceinline__ unsigned cvt_pk_bf16(float lo, float hi) { unsigned r; asm volatile("v_cvt_pk_bf16_f32 %0, %1, %2" : "=v"(r) : "v"(lo), "v"(hi)); return r; }
; __device__ __forceinline__ void phase_attn_combine(const Params& p) {
;     ...
;     for (int task = gtid; task < 200 * 4096; task += nthr) {
;         const int item = task >> 12, rc = task & 4095, row = rc >> 4, ch = rc & 15, head = item / 25, qb = 8 + item % 25;
;         const float* O0 = Ob + (size_t)(item * 2) * (256 * 128) + row * 128 + ch * 8; const float* O1 = O0 + 256 * 128;
;         const float m0 = MLb[(item * 2) * 512 + row * 2], l0 = MLb[(item * 2) * 512 + row * 2 + 1], m1 = MLb[(item * 2 + 1) * 512 + row * 2], l1 = MLb[(item * 2 + 1) * 512 + row * 2 + 1];
;         const float m = fmaxf(m0, m1), w0 = __builtin_amdgcn_exp2f(m0 - m), w1 = __builtin_amdgcn_exp2f(m1 - m);
;         const float inv = __builtin_amdgcn_rcpf(fmaxf(l0 * w0 + l1 * w1, 1e-30f));
;         const f32x4 a0 = __builtin_nontemporal_load((const f32x4*)O0), a1 = __builtin_nontemporal_load((const f32x4*)(O0 + 4)), b0 = __builtin_nontemporal_load((const f32x4*)O1), b1 = __builtin_nontemporal_load((const f32x4*)(O1 + 4));
;         const f32x4 x = (a0 * w0 + b0 * w1) * inv, y = (a1 * w0 + b1 * w1) * inv;
;         u32x4 w; w.x = cvt_pk_bf16(x[0], x[1]); w.y = cvt_pk_bf16(x[2], x[3]); w.z = cvt_pk_bf16(y[0], y[1]); w.w = cvt_pk_bf16(y[2], y[3]);
;         *(u32x4*)(Cat + (size_t)(qb * 256 + row) * DM + head * 128 + ch * 8) = w;
;     }
.LBB0_925:
	v_ashrrev_i32_e32 v6, 12, v2
	s_mov_b32 s2, 0x51eb851f
	v_mul_hi_i32 v0, v6, s2
	v_lshrrev_b32_e32 v4, 31, v0
	v_ashrrev_i32_e32 v0, 3, v0
	v_add_u32_e32 v24, v0, v4
	v_lshlrev_b32_e32 v4, 1, v6
	v_ashrrev_i32_e32 v5, 31, v4
	v_bfe_u32 v23, v2, 4, 8
	v_mul_lo_u32 v0, v24, 25
	v_lshlrev_b64 v[4:5], 17, v[4:5]
	v_sub_u32_e32 v25, v6, v0
	v_lshl_add_u64 v[4:5], s[44:45], 0, v[4:5]
	v_lshlrev_b32_e32 v0, 9, v23
	v_and_b32_e32 v26, 0x78, v3
	v_lshl_add_u64 v[4:5], v[4:5], 0, v[0:1]
	v_lshlrev_b32_e32 v0, 2, v26
	v_lshl_add_u64 v[12:13], v[4:5], 0, v[0:1]
	v_lshlrev_b32_e32 v0, 10, v6
	v_lshl_or_b32 v4, v23, 1, v0
	v_ashrrev_i32_e32 v5, 31, v4
	v_lshl_add_u64 v[4:5], v[4:5], 2, s[10:11]
	global_load_dwordx2 v[28:29], v[4:5], off
	global_load_dwordx2 v[30:31], v[4:5], off offset:2048
	s_mov_b32 s2, 0x20000
	v_lshl_add_u64 v[16:17], v[12:13], 0, s[84:85]
	v_add_u32_e32 v2, s30, v2
	v_add_u32_e32 v3, s25, v3
	global_load_dwordx4 v[4:7], v[12:13], off offset:16 nt
	global_load_dwordx4 v[8:11], v[12:13], off nt
	v_add_co_u32_e32 v12, vcc, s2, v12
	s_nop 1
	v_addc_co_u32_e32 v13, vcc, 0, v13, vcc
	global_load_dwordx4 v[12:15], v[12:13], off nt
	s_nop 0
	global_load_dwordx4 v[16:19], v[16:17], off offset:16 nt
	s_waitcnt vmcnt(4)
	v_max_f32_e32 v32, v28, v28
	v_max_f32_e32 v0, v30, v30
	v_max_f32_e32 v0, v32, v0
	v_sub_f32_e32 v28, v28, v0
	v_sub_f32_e32 v0, v30, v0
	v_exp_f32_e32 v20, v28
	v_exp_f32_e32 v21, v0
	v_mov_b32_e32 v32, v29
	v_mov_b32_e32 v33, v31
	v_pk_mul_f32 v[32:33], v[32:33], v[20:21]
	s_nop 0
	v_add_f32_e32 v0, v32, v33
	v_max_f32_e32 v0, 0xda24260, v0
	s_nop 0
	v_rcp_f32_e32 v0, v0
	v_mov_b32_e32 v22, v21
	s_mov_b32 s2, 0xc7fff
	v_cmp_lt_i32_e32 vcc, s2, v2
	s_or_b64 s[4:5], vcc, s[4:5]
	s_waitcnt vmcnt(1)
	v_pk_mul_f32 v[14:15], v[14:15], v[22:23] op_sel_hi:[1,0]
	v_pk_mul_f32 v[12:13], v[12:13], v[22:23] op_sel_hi:[1,0]
	v_pk_fma_f32 v[10:11], v[10:11], v[20:21], v[14:15] op_sel_hi:[1,0,1]
	v_pk_fma_f32 v[8:9], v[8:9], v[20:21], v[12:13] op_sel_hi:[1,0,1]
	s_waitcnt vmcnt(0)
	v_pk_mul_f32 v[12:13], v[18:19], v[22:23] op_sel_hi:[1,0]
	v_pk_mul_f32 v[14:15], v[16:17], v[22:23] op_sel_hi:[1,0]
	v_pk_fma_f32 v[6:7], v[6:7], v[20:21], v[12:13] op_sel_hi:[1,0,1]
	v_pk_fma_f32 v[4:5], v[4:5], v[20:21], v[14:15] op_sel_hi:[1,0,1]
	v_pk_mul_f32 v[10:11], v[10:11], v[0:1] op_sel_hi:[1,0]
	v_pk_mul_f32 v[8:9], v[8:9], v[0:1] op_sel_hi:[1,0]
	v_pk_mul_f32 v[12:13], v[6:7], v[0:1] op_sel_hi:[1,0]
	v_pk_mul_f32 v[6:7], v[4:5], v[0:1] op_sel_hi:[1,0]
	v_lshl_or_b32 v0, v25, 8, v23
	v_cvt_pk_bf16_f32 v4, v8, v9
	v_add_u32_e32 v8, 0x800, v0
	v_ashrrev_i32_e32 v9, 31, v8
	v_cvt_pk_bf16_f32 v5, v10, v11
	v_lshlrev_b64 v[8:9], 12, v[8:9]
	v_lshlrev_b32_e32 v10, 7, v24
	v_lshl_add_u64 v[8:9], s[16:17], 0, v[8:9]
	v_ashrrev_i32_e32 v11, 31, v10
	v_lshl_add_u64 v[8:9], v[10:11], 1, v[8:9]
	v_lshlrev_b32_e32 v0, 1, v26
	v_lshl_add_u64 v[8:9], v[8:9], 0, v[0:1]
	v_cvt_pk_bf16_f32 v6, v6, v7
	v_cvt_pk_bf16_f32 v7, v12, v13
	global_store_dwordx4 v[8:9], v[4:7], off
	s_andn2_b64 exec, exec, s[4:5]
	s_cbranch_execnz .LBB0_925
